# P2: the forget-gate scan of workgroups 0..63 moved behind the GEMM prologue's first LDS-DMA stage (its load latency now overlaps the DMA latency); registers renamed, scratch words moved to the unused
# speedup vs baseline: 1.0198x; 1.0019x over previous
;     __device__ __forceinline__ long a_off(int pm, size_t tstep) const { return (long)pm * (long)tstep; }
; #define PG8_STAGE(bufoff, gbase, voff) do { _Pragma("unroll") for (int _i = 0; _i < 2; ++_i) \
;         __builtin_amdgcn_global_load_lds((const unsigned*)((const char*)(gbase) + (voff)[_i]), (PG8_LAS unsigned*)(lds + (bufoff) + ldsw + _i * 8192), 16, 0, 0); } while (0)
; #define PG8_WAIT_V(n) asm volatile("s_waitcnt vmcnt(" #n ")" ::: "memory")
; #define PG8_BAR __builtin_amdgcn_s_barrier()
; template <class Epi, class Sched, bool ALIGN_EPI = false, bool SP2 = false>
; __device__ __forceinline__ void gemm_phase(PG8_LAS unsigned char* lds, const Gemm g, const Sched& S, const Epi& E) {
;     ...
;     const int tid = tid_o & 511, wid = __builtin_amdgcn_readfirstlane(tid >> 6), lane = tid & 63, wr = wid >> 2, wc = wid & 3, fr = lane & 15, fq = lane >> 4;
;     const int K = g.K, nt = K / BK;
;     unsigned voffA[2], voffB[2];
; #pragma unroll
;     for (int i = 0; i < 2; ++i) { int R, C; stage_rc(tid * 16 + i * 8192, R, C); const int Rb = Epi::PERM ? ((R & ~31) + perm32(R & 31)) : R;
;         voffA[i] = (unsigned)(R * K + C) * 2u; voffB[i] = (unsigned)(Rb * K + C) * 2u; }
;     const size_t kstep = (size_t)(BK * 2);
;     const size_t hstep = (size_t)HALF * K * 2;
;     const size_t tstep = 2 * hstep;
;     const unsigned ldsw = (unsigned)wid * 1024u;
;     const int aoff = lds_byte(wr * 64 + fr, fq * 8), boff = lds_byte(wc * 32 + fr, fq * 8);
;     ...
;     const char* cA = (const char*)g.A + S.a_off(cur.pm, tstep); const char* cB = (const char*)g.Bt + (size_t)cur.pn * tstep;
;     S.a_ready(cur);
;     if constexpr (SP2) {
;         PG8_STAGE(PG8_SB(0, 0), cB, voffB); PG8_STAGE(PG8_SB(0, 1), cB + hstep, voffB); PG8_STAGE(PG8_SA(0, 0), cA, voffA); PG8_STAGE(PG8_SA(0, 1), cA + hstep, voffA);
;         if (wr == 1) PG8_BAR;
;         PG8_WAIT_V(2); PG8_BAR;
;         PG8_STAGE(PG8_SB(1, 0), cB + kstep, voffB); PG8_STAGE(PG8_SA(1, 0), cA + kstep, voffA); PG8_STAGE(PG8_SB(1, 1), cB + hstep + kstep, voffB);
;         PG8_WAIT_V(6); PG8_BAR;
;     } else {
;         PG8_STAGE(PG8_SB(0, 0), cB, voffB); PG8_STAGE(PG8_SA(0, 0), cA, voffA); PG8_STAGE(PG8_SB(0, 1), cB + hstep, voffB); PG8_STAGE(PG8_SA(0, 1), cA + hstep, voffA);
;         if (wr == 1) PG8_BAR;
.Lgb2_done:
.LBB0_253:
	s_or_b64 exec, exec, s[8:9]
	s_waitcnt lgkmcnt(0)
	s_barrier
	s_load_dwordx2 s[4:5], s[96:97], 0
	s_load_dwordx2 s[8:9], s[96:97], 8
	s_load_dwordx2 s[10:11], s[96:97], 16
	s_load_dwordx2 s[12:13], s[96:97], 24
	s_load_dwordx2 s[14:15], s[96:97], 32
	s_load_dwordx2 s[16:17], s[96:97], 40
	s_load_dwordx2 s[18:19], s[96:97], 48
	s_load_dwordx2 s[30:31], s[96:97], 56
	s_load_dwordx2 s[34:35], s[96:97], 64
	s_load_dwordx2 s[20:21], s[96:97], 72
	s_load_dwordx2 s[22:23], s[96:97], 80
	s_load_dwordx2 s[28:29], s[96:97], 88
	s_load_dwordx2 s[38:39], s[96:97], 96
	s_load_dwordx2 s[40:41], s[96:97], 104
	s_load_dwordx2 s[42:43], s[96:97], 112
	s_load_dwordx2 s[44:45], s[96:97], 120
	s_load_dwordx2 s[36:37], s[96:97], 128
	s_waitcnt lgkmcnt(0)
.LBB0_265:
	v_mov_b32_e32 v12, v208
	s_cmpk_gt_i32 s2, 0x2ff
	v_and_b32_e32 v8, 0x1ff, v12
	s_nop 0
	v_readfirstlane_b32 s9, v8
	s_cbranch_scc1 .LBB0_293
	s_add_u32 s3, s36, 0x2000000
	v_lshrrev_b32_e32 v0, 5, v12
	v_lshrrev_b32_e32 v14, 1, v12
	s_addc_u32 s4, s37, 0
	v_and_b32_e32 v0, 4, v0
	v_bfe_u32 v1, v12, 2, 2
	v_and_b32_e32 v2, 24, v14
	v_lshrrev_b32_e32 v9, 3, v8
	s_add_u32 s5, s36, 0x600000
	v_or3_b32 v0, v0, v1, v2
	v_or_b32_e32 v1, 64, v9
	s_movk_i32 s0, 0x60
	s_addc_u32 s28, s37, 0
	v_and_or_b32 v2, v1, s0, v0
	v_bfe_u32 v13, v12, 2, 4
	s_movk_i32 s0, 0x70
	s_ashr_i32 s54, s2, 31
	v_and_or_b32 v1, v1, s0, v13
	s_lshr_b32 s0, s54, 29
	s_add_i32 s0, s2, s0
	s_lshr_b32 s17, s9, 6
	s_ashr_i32 s1, s0, 3
	s_and_b32 s0, s0, -8
	s_lshr_b32 s13, s9, 8
	s_lshl_b32 s29, s17, 10
	s_sub_i32 s0, s2, s0
	s_cmp_lt_i32 s0, 0
	s_movk_i32 s55, 0x61
	s_cselect_b32 s8, s55, 0x60
	s_mul_i32 s0, s0, s8
	s_add_i32 s0, s0, s1
	s_mul_hi_i32 s1, s0, 0x2aaaaaab
	s_lshr_b32 s8, s1, 31
	s_ashr_i32 s1, s1, 4
	s_add_i32 s1, s1, s8
	s_lshl_b32 s10, s1, 3
	s_mulk_i32 s1, 0x60
	s_sub_i32 s0, s0, s1
	s_bfe_i32 s1, s0, 0x80000
	s_bfe_u32 s1, s1, 0x3000c
	s_add_i32 s1, s0, s1
	s_bfe_i32 s8, s1, 0x80000
	s_and_b32 s1, s1, 0xf8
	s_sub_i32 s0, s0, s1
	s_sext_i32_i16 s8, s8
	s_sext_i32_i8 s0, s0
	s_lshr_b32 s8, s8, 3
	s_add_i32 s20, s10, s0
	s_ashr_i32 s21, s20, 31
	s_bfe_i64 s[14:15], s[8:9], 0x100000
	v_lshlrev_b32_e32 v3, 4, v8
	v_and_b32_e32 v4, 32, v12
	s_lshl_b64 s[10:11], s[20:21], 19
	s_lshl_b64 s[14:15], s[14:15], 19
	v_bitop3_b32 v10, v3, v4, 48 bitop3:0x6c
	v_and_b32_e32 v11, 64, v12
	s_add_u32 s50, s5, s14
	v_or_b32_e32 v3, v10, v11
	v_and_or_b32 v0, v9, 32, v0
	s_addc_u32 s51, s28, s15
	s_add_i32 s56, s29, 0
	v_lshl_or_b32 v132, v0, 11, v3
	s_add_i32 m0, s56, 0x10000
	v_lshl_or_b32 v128, v2, 11, v3
	global_load_lds_dwordx4 v132, s[50:51]
	s_add_i32 m0, s56, 0x12000
	s_add_u32 s14, s50, 0x40000
	global_load_lds_dwordx4 v128, s[50:51]
	s_addc_u32 s15, s51, 0
	s_add_i32 m0, s56, 0x14000
	v_and_or_b32 v0, v9, 48, v13
	global_load_lds_dwordx4 v132, s[14:15]
	s_add_i32 m0, s56, 0x16000
	v_lshl_or_b32 v134, v0, 11, v3
	global_load_lds_dwordx4 v128, s[14:15]
	s_add_u32 s14, s3, s10
	s_addc_u32 s15, s4, s11
	s_add_i32 s57, s56, 0x2000
	s_mov_b32 m0, s56
	s_add_u32 s10, s14, 0x40000
	v_lshl_or_b32 v130, v1, 11, v3
	global_load_lds_dwordx4 v134, s[14:15]
	s_mov_b32 m0, s57
	s_addc_u32 s11, s15, 0
	s_add_i32 s59, s56, 0x4000
	global_load_lds_dwordx4 v130, s[14:15]
	s_mov_b32 m0, s59
	s_add_i32 s60, s56, 0x6000
	global_load_lds_dwordx4 v134, s[10:11]
	s_mov_b32 m0, s60
	v_mov_b32_e32 v137, 0
	global_load_lds_dwordx4 v130, s[10:11]
	v_mov_b32_e32 v133, v137
	v_mov_b32_e32 v129, v137
	v_mov_b32_e32 v135, v137
	v_mov_b32_e32 v131, v137
	s_cmp_eq_u32 s13, 1
	s_mov_b32 s61, 0
	v_lshl_add_u64 v[6:7], s[50:51], 0, v[132:133]
	v_lshl_add_u64 v[4:5], s[50:51], 0, v[128:129]
	v_lshl_add_u64 v[2:3], s[14:15], 0, v[134:135]
	v_lshl_add_u64 v[0:1], s[14:15], 0, v[130:131]
	s_movk_i32 s62, 0x2000
	s_movk_i32 s63, 0x4000
	s_cselect_b64 s[10:11], -1, 0
	s_cmp_lg_u32 s13, 1
	s_movk_i32 s64, 0x6000
	s_cbranch_scc1 .LBB0_268
	s_barrier
.LBB0_268:
	s_add_u32 s65, s36, 0x6000000
	s_addc_u32 s66, s37, 0
	s_add_u32 s12, s36, 0x7000000
	s_addc_u32 s0, s37, 0
	s_add_u32 s16, s36, 0x8000000
	s_mov_b64 s[38:39], 0x80
	s_addc_u32 s1, s37, 0
	s_and_b32 s67, s17, 3
	s_add_i32 m0, s56, 0x18000
	v_lshl_add_u64 v[6:7], v[6:7], 0, s[38:39]
	s_lshl_b32 s68, s13, 6
	s_lshl_b32 s13, s13, 13
	s_lshl_b32 s17, s67, 12
	s_cmp_gt_i32 s2, 63
	s_cbranch_scc1 .Lscan_skip
; #define LAS __attribute__((address_space(3)))
; __device__ __forceinline__ void scan_item(const Params& p, LAS unsigned char* lds, int bh, int tid, int lane, int wave) {
;     const float* logf = (const float*)(p.ws + WS_LOGF); const int b = bh >> 3, h = bh & 7;
;     LAS float* wt = (LAS float*)lds;
;     float a[4];
; #pragma unroll
;     for (int i = 0; i < 4; ++i) a[i] = logf[((size_t)(b * S_ + 4 * tid + i)) * 8 + h];
;     a[1] += a[0]; a[2] += a[1]; a[3] += a[2];
;     float sc = a[3];
; #pragma unroll
;     for (int o = 1; o < 64; o <<= 1) { const float y = __shfl_up(sc, o); if (lane >= o) sc += y; }
;     if (lane == 63) wt[wave] = sc;
;     __syncthreads();
;     float off = sc - a[3];
;     for (int w = 0; w < wave; ++w) off += wt[w];
	v_readfirstlane_b32 s76, v208
	s_and_b32 s74, s2, 7
	s_lshl_b32 s75, s2, 8
	s_and_b32 s75, s75, 0xfffff800
	s_lshl_b32 s74, s74, 2
	v_add_u32_e32 v16, s75, v96
	s_add_u32 s74, s36, s74
	s_addc_u32 s75, s37, 0
	v_or_b32_e32 v20, 1, v16
	s_add_u32 s78, s74, 0x100000
	v_ashrrev_i32_e32 v21, 31, v20
	s_addc_u32 s79, s75, 0
	v_ashrrev_i32_e32 v17, 31, v16
	v_lshlrev_b64 v[20:21], 5, v[20:21]
	v_lshlrev_b64 v[18:19], 5, v[16:17]
	v_lshl_add_u64 v[22:23], s[78:79], 0, v[20:21]
	v_or_b32_e32 v20, 2, v16
	v_or_b32_e32 v16, 3, v16
	v_ashrrev_i32_e32 v21, 31, v20
	v_ashrrev_i32_e32 v17, 31, v16
	v_lshl_add_u64 v[18:19], s[78:79], 0, v[18:19]
	v_lshlrev_b64 v[20:21], 5, v[20:21]
	v_lshlrev_b64 v[16:17], 5, v[16:17]
	v_lshl_add_u64 v[24:25], s[78:79], 0, v[20:21]
	v_lshl_add_u64 v[16:17], s[78:79], 0, v[16:17]
	global_load_dword v20, v[18:19], off
	global_load_dword v21, v[22:23], off
	global_load_dword v26, v[24:25], off
	global_load_dword v27, v[16:17], off
	v_mbcnt_hi_u32_b32 v19, -1, v209
	v_and_b32_e32 v22, 64, v19
	v_add_u32_e32 v16, -1, v19
	v_cmp_lt_i32_e32 vcc, v16, v22
	v_add_u32_e32 v24, -4, v19
	s_waitcnt vmcnt(2)
	v_add_f32_e32 v18, v20, v21
	v_cndmask_b32_e32 v16, v16, v19, vcc
	s_waitcnt vmcnt(1)
	v_add_f32_e32 v17, v26, v18
	v_lshlrev_b32_e32 v23, 2, v16
	s_waitcnt vmcnt(0)
	v_add_f32_e32 v16, v27, v17
	ds_bpermute_b32 v21, v23, v16
	v_add_u32_e32 v23, -2, v19
	v_cmp_lt_i32_e32 vcc, v23, v22
	s_waitcnt lgkmcnt(0)
	v_add_f32_e32 v21, v16, v21
	v_cndmask_b32_e32 v23, v23, v19, vcc
	v_cmp_eq_u32_e32 vcc, 0, v154
	v_lshlrev_b32_e32 v23, 2, v23
	s_nop 0
	v_cndmask_b32_e32 v21, v21, v16, vcc
	ds_bpermute_b32 v23, v23, v21
	v_cmp_lt_i32_e32 vcc, v24, v22
	s_waitcnt lgkmcnt(0)
	v_add_f32_e32 v23, v21, v23
	v_cndmask_b32_e32 v24, v24, v19, vcc
	v_cmp_gt_u32_e32 vcc, 2, v154
	v_lshlrev_b32_e32 v24, 2, v24
	s_nop 0
	v_cndmask_b32_e32 v21, v23, v21, vcc
	ds_bpermute_b32 v23, v24, v21
	v_add_u32_e32 v24, -8, v19
	v_cmp_lt_i32_e32 vcc, v24, v22
	s_waitcnt lgkmcnt(0)
	v_add_f32_e32 v23, v21, v23
	v_cndmask_b32_e32 v24, v24, v19, vcc
	v_cmp_gt_u32_e32 vcc, 4, v154
	v_lshlrev_b32_e32 v24, 2, v24
	s_nop 0
	v_cndmask_b32_e32 v21, v23, v21, vcc
	ds_bpermute_b32 v23, v24, v21
	v_add_u32_e32 v24, -16, v19
	v_cmp_lt_i32_e32 vcc, v24, v22
	s_waitcnt lgkmcnt(0)
	v_add_f32_e32 v23, v21, v23
	v_cndmask_b32_e32 v24, v24, v19, vcc
	v_cmp_gt_u32_e32 vcc, 8, v154
	v_lshlrev_b32_e32 v24, 2, v24
	s_nop 0
	v_cndmask_b32_e32 v21, v23, v21, vcc
	ds_bpermute_b32 v23, v24, v21
	v_subrev_u32_e32 v24, 32, v19
	v_cmp_lt_i32_e32 vcc, v24, v22
	s_nop 1
	v_cndmask_b32_e32 v19, v24, v19, vcc
	v_lshlrev_b32_e32 v22, 2, v19
	s_waitcnt lgkmcnt(0)
	v_add_f32_e32 v19, v21, v23
	v_cmp_gt_u32_e32 vcc, 16, v154
	s_nop 1
	v_cndmask_b32_e32 v19, v19, v21, vcc
	ds_bpermute_b32 v21, v22, v19
	v_cmp_eq_u32_e32 vcc, 63, v154
	s_waitcnt lgkmcnt(0)
	v_add_f32_e32 v21, v19, v21
	s_and_saveexec_b64 s[80:81], vcc
	s_lshl_b32 s74, s58, 2
	s_add_i32 s74, s74, 0x20040
	v_mov_b32_e32 v22, s74
	ds_write_b32 v22, v21
	s_or_b64 exec, exec, s[80:81]
	v_cndmask_b32_e64 v19, v21, v19, s[6:7]
	s_cmp_lt_u32 s76, 64
	v_sub_f32_e32 v19, v19, v16
	s_waitcnt lgkmcnt(0)
	s_barrier
	s_cbranch_scc1 .LBB0_264
	s_add_i32 s74, s58, -1
	s_cmp_lt_u32 s74, 7
	s_cbranch_scc1 .LBB0_261
	s_and_b32 s78, s58, 0x3fffff8
	s_mov_b32 s79, 0
	s_mov_b32 s80, 0x20040
.LBB0_259:
	v_mov_b32_e32 v21, s80
	ds_read_b128 v[22:25], v21
	ds_read_b128 v[26:29], v21 offset:16
	s_add_i32 s79, s79, 8
	s_add_i32 s80, s80, 32
	s_cmp_lg_u32 s78, s79
	s_waitcnt lgkmcnt(1)
	v_add_f32_e32 v19, v19, v22
	v_add_f32_e32 v19, v19, v23
	v_add_f32_e32 v19, v19, v24
	v_add_f32_e32 v19, v19, v25
	s_waitcnt lgkmcnt(0)
	v_add_f32_e32 v19, v19, v26
	v_add_f32_e32 v19, v19, v27
	v_add_f32_e32 v19, v19, v28
	v_add_f32_e32 v19, v19, v29
	s_cbranch_scc1 .LBB0_259
	s_bfe_u32 s76, s76, 0x30006
	s_cmp_eq_u32 s76, 0
	s_cbranch_scc0 .LBB0_262
	s_branch .LBB0_264
.LBB0_261:
	s_mov_b32 s78, 0
	s_bfe_u32 s76, s76, 0x30006
	s_cmp_eq_u32 s76, 0
	s_cbranch_scc1 .LBB0_264
.LBB0_262:
	s_lshl_b32 s74, s78, 2
	s_add_i32 s78, s74, 0x20040
.LBB0_263:
	v_mov_b32_e32 v21, s78
	ds_read_b32 v21, v21
	s_add_i32 s78, s78, 4
	s_add_i32 s76, s76, -1
	s_cmp_lg_u32 s76, 0
	s_waitcnt lgkmcnt(0)
	v_add_f32_e32 v19, v19, v21
	s_cbranch_scc1 .LBB0_263
; __device__ __forceinline__ unsigned f2bf(float f) { unsigned u = __builtin_bit_cast(unsigned, f); return (u + 0x7fffu + ((u >> 16) & 1u)) >> 16; }
; __device__ __forceinline__ void scan_item(const Params& p, LAS unsigned char* lds, int bh, int tid, int lane, int wave) {
;     ...
;     u32x4* qa = (u32x4*)(p.ws + WS_QAUG) + (size_t)bh * S_ + 4 * tid; u32x4* ka = (u32x4*)(p.ws + WS_KAUG) + (size_t)bh * S_ + 4 * tid;
; #pragma unroll
;     for (int i = 0; i < 4; ++i) { const float F = (off + a[i]) * LOG2E;
;         const unsigned hi = f2bf(F); const float r1 = F - bf2f(hi); const unsigned mid = f2bf(r1); const float r2 = r1 - bf2f(mid); const unsigned lo = f2bf(r2);
;         u32x4 q, k; q.x = hi | (mid << 16); q.y = lo | (0x3F80u << 16); q.z = 0x3F803F80u; q.w = 0u;
;         k.x = 0x3F803F80u; k.y = 0x3F80u | ((hi ^ 0x8000u) << 16); k.z = (mid ^ 0x8000u) | ((lo ^ 0x8000u) << 16); k.w = 0u;
;         qa[i] = q; ka[i] = k; }
;     __syncthreads();
.LBB0_264:
	s_mov_b32 s84, s2
	s_ashr_i32 s85, s2, 31
	s_lshl_b64 s[78:79], s[84:85], 15
	s_add_u32 s78, s36, s78
	v_add_f32_e32 v20, v20, v19
	v_lshlrev_b32_e32 v22, 4, v96
	v_mov_b32_e32 v23, 0
	s_addc_u32 s79, s37, s79
	v_mul_f32_e32 v21, 0x3fb8aa3b, v20
	v_lshl_add_u64 v[28:29], s[78:79], 0, v[22:23]
	v_bfe_u32 v22, v21, 16, 1
	s_movk_i32 s75, 0x7fff
	v_add3_u32 v24, v21, v22, s75
	s_mov_b32 s74, 0x3fb8aa3b
	v_and_b32_e32 v21, 0xffff0000, v24
	v_fma_f32 v20, v20, s74, -v21
	v_bfe_u32 v21, v20, 16, 1
	v_add3_u32 v21, v20, v21, s75
	v_lshrrev_b32_e32 v25, 16, v21
	v_and_b32_e32 v21, 0xffff0000, v21
	v_sub_f32_e32 v20, v20, v21
	v_bfe_u32 v22, v20, 16, 1
	s_mov_b64 s[78:79], 0x200000
	v_add3_u32 v26, v20, v22, s75
	v_mov_b32_e32 v36, 1.0
	v_lshl_add_u64 v[30:31], v[28:29], 0, s[78:79]
	s_mov_b64 s[78:79], 0x400000
	v_or_b32_sdwa v27, v21, v24 dst_sel:DWORD dst_unused:UNUSED_PAD src0_sel:DWORD src1_sel:WORD_1
	v_or_b32_sdwa v34, v26, v36 dst_sel:DWORD dst_unused:UNUSED_PAD src0_sel:WORD_1 src1_sel:DWORD
	s_mov_b32 s83, 0
	s_mov_b32 s82, 0x3f803f80
	v_mov_b64_e32 v[20:21], s[80:81]
	s_mov_b32 s76, 0x80003f80
	v_mov_b32_e32 v37, 0xffff0000
	v_lshl_add_u64 v[32:33], v[28:29], 0, s[78:79]
	v_mov_b64_e32 v[22:23], s[82:83]
	v_mov_b32_e32 v21, v34
	v_bitop3_b32 v34, v24, s76, v37 bitop3:0x6c
	v_and_b32_e32 v24, 0xffff0000, v26
	s_mov_b32 s78, 0x80008000
	s_mov_b32 s80, s82
	v_mov_b32_e32 v20, v27
	v_bitop3_b32 v35, v24, s78, v25 bitop3:0x36
	v_mov_b64_e32 v[24:25], s[80:81]
	s_mov_b32 s79, 0x200000
	v_mov_b64_e32 v[26:27], s[82:83]
	v_mov_b32_e32 v25, v34
	v_add_co_u32_e32 v34, vcc, s79, v28
	v_mov_b32_e32 v26, v35
	s_nop 0
	v_addc_co_u32_e32 v35, vcc, 0, v29, vcc
	s_mov_b32 s79, 0x400000
	global_store_dwordx4 v[34:35], v[20:23], off sc1
	v_add_f32_e32 v18, v18, v19
	v_add_f32_e32 v17, v17, v19
	v_add_co_u32_e32 v20, vcc, s79, v28
	v_add_f32_e32 v16, v16, v19
	s_nop 0
	v_addc_co_u32_e32 v21, vcc, 0, v29, vcc
	global_store_dwordx4 v[20:21], v[24:27], off sc1
	v_mul_f32_e32 v20, 0x3fb8aa3b, v18
	v_bfe_u32 v21, v20, 16, 1
	v_add3_u32 v24, v20, v21, s75
	v_and_b32_e32 v20, 0xffff0000, v24
	v_fma_f32 v18, v18, s74, -v20
	v_bfe_u32 v20, v18, 16, 1
	v_add3_u32 v20, v18, v20, s75
	v_lshrrev_b32_e32 v25, 16, v20
	v_and_b32_e32 v20, 0xffff0000, v20
	v_sub_f32_e32 v18, v18, v20
	v_bfe_u32 v21, v18, 16, 1
	v_add3_u32 v18, v18, v21, s75
	v_or_b32_sdwa v26, v20, v24 dst_sel:DWORD dst_unused:UNUSED_PAD src0_sel:DWORD src1_sel:WORD_1
	v_or_b32_sdwa v27, v18, v36 dst_sel:DWORD dst_unused:UNUSED_PAD src0_sel:WORD_1 src1_sel:DWORD
	v_mov_b64_e32 v[20:21], s[80:81]
	v_and_b32_e32 v18, 0xffff0000, v18
	v_mov_b32_e32 v20, v26
	v_mov_b32_e32 v21, v27
	v_bitop3_b32 v28, v24, s76, v37 bitop3:0x6c
	v_bitop3_b32 v18, v18, s78, v25 bitop3:0x36
	v_mov_b64_e32 v[24:25], s[80:81]
	v_mov_b64_e32 v[26:27], s[82:83]
	v_mov_b64_e32 v[22:23], s[82:83]
	v_mov_b32_e32 v26, v18
	v_mul_f32_e32 v18, 0x3fb8aa3b, v17
	v_mov_b32_e32 v25, v28
	global_store_dwordx4 v[30:31], v[20:23], off offset:16 sc1
	global_store_dwordx4 v[32:33], v[24:27], off offset:16 sc1
	s_nop 0
	v_bfe_u32 v20, v18, 16, 1
	v_add3_u32 v18, v18, v20, s75
	v_and_b32_e32 v20, 0xffff0000, v18
	v_fma_f32 v17, v17, s74, -v20
	v_bfe_u32 v20, v17, 16, 1
	v_add3_u32 v20, v17, v20, s75
	v_lshrrev_b32_e32 v24, 16, v20
	v_and_b32_e32 v20, 0xffff0000, v20
	v_sub_f32_e32 v17, v17, v20
	v_bfe_u32 v21, v17, 16, 1
	v_add3_u32 v17, v17, v21, s75
	v_or_b32_sdwa v25, v20, v18 dst_sel:DWORD dst_unused:UNUSED_PAD src0_sel:DWORD src1_sel:WORD_1
	v_or_b32_sdwa v26, v17, v36 dst_sel:DWORD dst_unused:UNUSED_PAD src0_sel:WORD_1 src1_sel:DWORD
	v_mov_b64_e32 v[20:21], s[80:81]
	v_and_b32_e32 v17, 0xffff0000, v17
	v_mov_b32_e32 v20, v25
	v_mov_b32_e32 v21, v26
	v_bitop3_b32 v17, v17, s78, v24 bitop3:0x36
	v_mov_b64_e32 v[24:25], s[80:81]
	v_mov_b64_e32 v[26:27], s[82:83]
	v_bitop3_b32 v18, v18, s76, v37 bitop3:0x6c
	v_mov_b32_e32 v26, v17
	v_mul_f32_e32 v17, 0x3fb8aa3b, v16
	v_mov_b64_e32 v[22:23], s[82:83]
	v_mov_b32_e32 v25, v18
	v_bfe_u32 v18, v17, 16, 1
	global_store_dwordx4 v[30:31], v[20:23], off offset:32 sc1
	global_store_dwordx4 v[32:33], v[24:27], off offset:32 sc1
	s_nop 0
	v_add3_u32 v20, v17, v18, s75
	v_and_b32_e32 v17, 0xffff0000, v20
	v_fma_f32 v16, v16, s74, -v17
	v_bfe_u32 v17, v16, 16, 1
	v_add3_u32 v17, v16, v17, s75
	v_lshrrev_b32_e32 v21, 16, v17
	v_and_b32_e32 v17, 0xffff0000, v17
	v_sub_f32_e32 v16, v16, v17
	v_bfe_u32 v18, v16, 16, 1
	v_add3_u32 v22, v16, v18, s75
	v_or_b32_sdwa v23, v17, v20 dst_sel:DWORD dst_unused:UNUSED_PAD src0_sel:DWORD src1_sel:WORD_1
	v_or_b32_sdwa v24, v22, v36 dst_sel:DWORD dst_unused:UNUSED_PAD src0_sel:WORD_1 src1_sel:DWORD
	v_mov_b64_e32 v[16:17], s[80:81]
	v_mov_b32_e32 v17, v24
	v_bitop3_b32 v24, v20, s76, v37 bitop3:0x6c
	v_and_b32_e32 v20, 0xffff0000, v22
	v_mov_b32_e32 v16, v23
	v_bitop3_b32 v25, v20, s78, v21 bitop3:0x36
	v_mov_b64_e32 v[20:21], s[80:81]
	v_mov_b64_e32 v[18:19], s[82:83]
	v_mov_b64_e32 v[22:23], s[82:83]
	v_mov_b32_e32 v21, v24
	v_mov_b32_e32 v22, v25
	global_store_dwordx4 v[30:31], v[16:19], off offset:48 sc1
	global_store_dwordx4 v[32:33], v[20:23], off offset:48 sc1
	s_branch .Lscan_join
; #define PG8_STAGE(bufoff, gbase, voff) do { _Pragma("unroll") for (int _i = 0; _i < 2; ++_i) \
;         __builtin_amdgcn_global_load_lds((const unsigned*)((const char*)(gbase) + (voff)[_i]), (PG8_LAS unsigned*)(lds + (bufoff) + ldsw + _i * 8192), 16, 0, 0); } while (0)
; #define PG8_WAIT_V(n) asm volatile("s_waitcnt vmcnt(" #n ")" ::: "memory")
; #define PG8_BAR __builtin_amdgcn_s_barrier()
; template <class Epi, class Sched, bool ALIGN_EPI = false, bool SP2 = false>
; __device__ __forceinline__ void gemm_phase(PG8_LAS unsigned char* lds, const Gemm g, const Sched& S, const Epi& E) {
;     ...
;     const int aoff = lds_byte(wr * 64 + fr, fq * 8), boff = lds_byte(wc * 32 + fr, fq * 8);
;     ...
;         PG8_STAGE(PG8_SB(0, 0), cB, voffB); PG8_STAGE(PG8_SB(0, 1), cB + hstep, voffB); PG8_STAGE(PG8_SA(0, 0), cA, voffA); PG8_STAGE(PG8_SA(0, 1), cA + hstep, voffA);
;         if (wr == 1) PG8_BAR;
;         PG8_WAIT_V(2); PG8_BAR;
;         PG8_STAGE(PG8_SB(1, 0), cB + kstep, voffB); PG8_STAGE(PG8_SA(1, 0), cA + kstep, voffA); PG8_STAGE(PG8_SB(1, 1), cB + hstep + kstep, voffB);
;         PG8_WAIT_V(6); PG8_BAR;
.Lscan_skip:
	s_waitcnt vmcnt(2)
.Lscan_join:
	s_barrier
	global_load_lds_dwordx4 v[6:7], off
	v_lshl_add_u64 v[4:5], v[4:5], 0, s[38:39]
	s_add_i32 m0, s56, 0x1a000
	s_add_i32 s69, s56, 0x8000
	s_add_i32 s70, s56, 0xa000
	global_load_lds_dwordx4 v[4:5], off
	v_lshl_add_u64 v[2:3], v[2:3], 0, s[38:39]
	s_mov_b32 m0, s69
	s_add_u32 s18, s50, 0x40080
	global_load_lds_dwordx4 v[2:3], off
	v_lshl_add_u64 v[0:1], v[0:1], 0, s[38:39]
	s_mov_b32 m0, s70
	s_addc_u32 s19, s51, 0
	global_load_lds_dwordx4 v[0:1], off
	s_add_i32 m0, s56, 0x1c000
	v_lshl_add_u64 v[0:1], s[18:19], 0, v[132:133]
	global_load_lds_dwordx4 v[0:1], off
	v_lshl_add_u64 v[0:1], s[18:19], 0, v[128:129]
	s_add_i32 m0, s56, 0x1e000
	v_and_b32_e32 v156, 15, v12
	global_load_lds_dwordx4 v[0:1], off
	v_bfe_u32 v1, v12, 4, 2
	v_lshlrev_b32_e32 v157, 4, v1
	v_lshlrev_b32_e32 v3, 2, v12
	v_lshl_or_b32 v2, v156, 6, v157
	v_and_b32_e32 v3, 32, v3
	v_bitop3_b32 v4, v2, s13, v3 bitop3:0xde
	v_bitop3_b32 v158, v2, s17, v3 bitop3:0xde
	v_lshlrev_b32_e32 v2, 1, v12
	v_and_b32_e32 v3, 3, v12
	v_lshlrev_b32_e32 v0, 3, v1
	v_and_b32_e32 v2, 8, v2
	v_and_or_b32 v3, v14, 4, v3
	v_lshlrev_b32_e32 v1, 14, v1
	v_or3_b32 v167, v3, v2, v1
	v_lshlrev_b32_e32 v1, 8, v8
	v_and_b32_e32 v1, 0x18000, v1
	v_lshlrev_b32_e32 v2, 11, v13
	s_cmpk_lt_u32 s9, 0x100
	v_or3_b32 v1, v10, v1, v2
	s_cselect_b64 s[40:41], -1, 0
	s_and_b32 s13, s0, 0xffff
	v_add_u32_e32 v138, v1, v11
	v_lshlrev_b32_e32 v1, 11, v9
	s_mov_b32 s0, 0x38000
	v_mov_b32_e32 v3, 0x20000
	s_waitcnt vmcnt(6)
	v_bitop3_b32 v1, v1, s0, v3 bitop3:0xc8
	v_lshl_or_b32 v159, s67, 6, v157
	s_mov_b32 s23, 0x20000
	s_brev_b32 s22, -2
	v_or3_b32 v1, v10, v1, v2
	s_add_i32 s74, 0, 0x10000
	s_add_i32 s75, 0, 0x14000
	s_sext_i32_i8 s21, s8
	v_or_b32_e32 v160, 0x4000, v159
	v_or_b32_e32 v161, 0x8000, v159
	v_or_b32_e32 v162, 0xc000, v159
	v_or_b32_e32 v163, 0x20000, v159
	s_mov_b32 s71, 0x24000
	v_or_b32_e32 v164, 0x24000, v159
	v_or_b32_e32 v165, 0x28000, v159
	v_or_b32_e32 v166, 0x2c000, v159
	v_or_b32_e32 v168, 0xfffffa00, v159
	s_ashr_i32 s72, s26, 31
	s_mov_b32 s73, s26
	s_and_b32 s17, s1, 0xffff
	s_mov_b32 s18, s22
	s_mov_b32 s19, s23
	v_mov_b32_e32 v139, v137
	v_add_u32_e32 v140, v1, v11
	v_mov_b32_e32 v141, v137
	v_mov_b64_e32 v[142:143], 0x300
	v_mov_b64_e32 v[144:145], 0x2ff
	v_add_u32_e32 v169, s74, v158
	v_add_u32_e32 v170, s75, v158
	v_add_u32_e32 v171, 0, v4
	s_movk_i32 s76, 0x7fff
	s_movk_i32 s77, 0x1000
	s_movk_i32 s78, 0x3000
	s_movk_i32 s79, 0x5000
	s_movk_i32 s80, 0x7000
	s_mov_b32 s81, 0x21000
	s_mov_b32 s82, 0x22000
	s_mov_b32 s83, 0x23000
	s_mov_b32 s84, 0x25000
	s_mov_b32 s85, 0x26000
	s_mov_b32 s86, 0x27000
	s_brev_b32 s87, 32
	v_lshlrev_b32_e32 v172, 2, v0
	v_mov_b32_e32 v173, 0x358637bd
	s_mov_b32 s88, 0x800000
	v_mov_b32_e32 v175, 0x3e38aa3b
	v_mbcnt_hi_u32_b32 v176, -1, v209
	s_barrier
	s_branch .LBB0_271
